# FoX loop: issue next-tile LDS-DMA after the tile's 16 ds_reads instead of right after the barrier
# speedup vs baseline: 1.0056x; 1.0056x over previous
; template <int DV, int NMAP>
; __device__ __forceinline__ void attn_unit(LAS unsigned char* lds, const bf16_t* U, bf16_t* MIX, const float* logf, int b, int h, int qb, float lam, float slope2, const float* gn, float outscale, const int tid) {
;     ...
;     for (int t = 0; t < NT; ++t) {
;         if (t + 1 < NT) { if (PER == 2) asm volatile("s_waitcnt vmcnt(2)\n\ts_barrier" ::: "memory"); else asm volatile("s_waitcnt vmcnt(4)\n\ts_barrier" ::: "memory"); }
;         else asm volatile("s_waitcnt vmcnt(0)\n\ts_barrier" ::: "memory");
;         if (t + 2 < NT) AT_DMA(t + 2, st2);
.LBB0_194:
	s_waitcnt vmcnt(2)
	s_barrier
	s_branch .Lfxl_post

; #define LAS __attribute__((address_space(3)))
; template <int DV, int NMAP>
; __device__ __forceinline__ void attn_unit(LAS unsigned char* lds, const bf16_t* U, bf16_t* MIX, const float* logf, int b, int h, int qb, float lam, float slope2, const float* gn, float outscale, const int tid) {
;     ...
;         if (t + 1 < NT) { if (PER == 2) asm volatile("s_waitcnt vmcnt(2)\n\ts_barrier" ::: "memory"); else asm volatile("s_waitcnt vmcnt(4)\n\ts_barrier" ::: "memory"); }
;         else asm volatile("s_waitcnt vmcnt(0)\n\ts_barrier" ::: "memory");
;         if (t + 2 < NT) AT_DMA(t + 2, st2);
;         if (64 * t <= qrow0 + 31) {
;             const LAS unsigned char* Kb = lds + AT_K + (st * NMAP + map) * AT_KT + r32 * 16;
;             const LAS unsigned char* Vb = lds + AT_V + st * VT + vofs;
;             f32x16 p0, p1;
;             {
;                 const LAS float* bp = bias + 64 * t + 4 * hi;
; #pragma unroll
;                 for (int g = 0; g < 4; ++g) { const f32x4 v = *(const LAS f32x4*)(bp + 8 * g), w = *(const LAS f32x4*)(bp + 32 + 8 * g);
;                     p0[4 * g] = v[0]; p0[4 * g + 1] = v[1]; p0[4 * g + 2] = v[2]; p0[4 * g + 3] = v[3]; p1[4 * g] = w[0]; p1[4 * g + 1] = w[1]; p1[4 * g + 2] = w[2]; p1[4 * g + 3] = w[3]; }
;             }
;             {
;                 bf16x8 kf[8];
; #pragma unroll
;                 for (int d0 = 0; d0 < 4; ++d0) { kf[2 * d0] = *(const LAS bf16x8*)(Kb + (2 * d0 + hi) * 1056); kf[2 * d0 + 1] = *(const LAS bf16x8*)(Kb + (2 * d0 + hi) * 1056 + 512); }
;                 __builtin_amdgcn_sched_barrier(0);
; #pragma unroll
;                 for (int d0 = 0; d0 < 4; ++d0) {
;                     p0 = __builtin_amdgcn_mfma_f32_32x32x16_bf16(kf[2 * d0], qr[d0], p0, 0, 0, 0);
;                     p1 = __builtin_amdgcn_mfma_f32_32x32x16_bf16(kf[2 * d0 + 1], qr[d0], p1, 0, 0, 0);
;                 }
;                 __builtin_amdgcn_sched_barrier(0);
;             }
;             if (64 * t + 63 > qrow0) {
;                 const int q = qrow0 + r32, kv0 = 64 * t + 4 * hi;
; #pragma unroll
;                 for (int r = 0; r < 16; ++r) { const int kv = kv0 + (r & 3) + 8 * (r >> 2); if (kv > q) p0[r] = -1e30f; if (kv + 32 > q) p1[r] = -1e30f; }
;             }
.Lfxl_post:
	s_sub_i32 s30, s61, 63
	s_cmp_gt_i32 s30, s60
	s_cbranch_scc1 .Lfxl_inact
.LBB0_200:
	s_mul_i32 s30, s62, 0x2100
	v_add_u32_e32 v107, s30, v143
	ds_read_b128 v[50:53], v106
	ds_read_b128 v[54:57], v106 offset:32
	ds_read_b128 v[34:37], v106 offset:128
	ds_read_b128 v[38:41], v106 offset:160
	ds_read_b128 v[58:61], v106 offset:64
	ds_read_b128 v[62:65], v106 offset:96
	ds_read_b128 v[42:45], v106 offset:192
	ds_read_b128 v[46:49], v106 offset:224
	ds_read_b128 v[82:85], v107 offset:8448
	ds_read_b128 v[86:89], v107 offset:8960
	ds_read_b128 v[90:93], v107 offset:10560
	ds_read_b128 v[94:97], v107 offset:11072
	ds_read_b128 v[108:111], v107 offset:12672
	ds_read_b128 v[112:115], v107 offset:13184
	ds_read_b128 v[116:119], v107 offset:14784
	ds_read_b128 v[136:139], v107 offset:15296
	s_add_i32 s30, s64, 2
	s_cmp_ge_u32 s30, s37
	s_cbranch_scc1 .Lfxl_go
	s_mul_i32 s30, s41, 0x2100
	s_add_i32 s30, s20, s30
	s_mov_b32 s31, m0
	s_mov_b32 m0, s30
	s_nop 0
	global_load_lds_dwordx4 v[102:103], off
	s_mov_b32 m0, s31
	s_lshl_b32 s30, s41, 13
	s_add_i32 s30, s30, s40
	s_mov_b32 s31, m0
	s_mov_b32 m0, s30
	s_nop 0
	global_load_lds_dwordx4 v[100:101], off
	s_mov_b32 m0, s31
.Lfxl_go:
	s_waitcnt lgkmcnt(7)
	v_mfma_f32_32x32x16_bf16 v[50:65], v[82:85], v[78:81], v[50:65]
	s_waitcnt lgkmcnt(6)
	v_mfma_f32_32x32x16_bf16 v[34:49], v[86:89], v[78:81], v[34:49]
	s_waitcnt lgkmcnt(5)
	v_mfma_f32_32x32x16_bf16 v[50:65], v[90:93], v[74:77], v[50:65]
	s_waitcnt lgkmcnt(4)
	v_mfma_f32_32x32x16_bf16 v[34:49], v[94:97], v[74:77], v[34:49]
	s_waitcnt lgkmcnt(3)
	v_mfma_f32_32x32x16_bf16 v[50:65], v[108:111], v[70:73], v[50:65]
	s_waitcnt lgkmcnt(2)
	v_mfma_f32_32x32x16_bf16 v[34:49], v[112:115], v[70:73], v[34:49]
	s_waitcnt lgkmcnt(1)
	v_mfma_f32_32x32x16_bf16 v[50:65], v[116:119], v[66:69], v[50:65]
	s_waitcnt lgkmcnt(0)
	v_mfma_f32_32x32x16_bf16 v[34:49], v[136:139], v[66:69], v[34:49]
	s_cmp_le_i32 s61, s36
	s_cbranch_scc1 .LBB0_202
	v_add_u32_e32 v82, s61, v130
	v_subrev_u32_e32 v84, 31, v82
	v_subrev_u32_e32 v83, 63, v82
	v_cmp_le_i32_e32 vcc, v84, v0
	s_nop 5
	v_cndmask_b32_e32 v34, v230, v34, vcc
	v_cmp_lt_i32_e32 vcc, v83, v0
	s_nop 1
	v_cndmask_b32_e32 v51, v230, v51, vcc
	v_cmp_le_i32_e32 vcc, v83, v0
	v_subrev_u32_e32 v83, 30, v82
	s_nop 0
	v_cndmask_b32_e32 v50, v230, v50, vcc
	v_cmp_le_i32_e32 vcc, v83, v0
	v_subrev_u32_e32 v83, 61, v82
	s_nop 0
	v_cndmask_b32_e32 v35, v230, v35, vcc
	v_cmp_le_i32_e32 vcc, v83, v0
	v_subrev_u32_e32 v83, 29, v82
	s_nop 0
	v_cndmask_b32_e32 v52, v230, v52, vcc
	v_cmp_le_i32_e32 vcc, v83, v0
	v_subrev_u32_e32 v83, 60, v82
	s_nop 0
	v_cndmask_b32_e32 v36, v230, v36, vcc
	v_cmp_le_i32_e32 vcc, v83, v0
	v_subrev_u32_e32 v83, 28, v82
	s_nop 0
	v_cndmask_b32_e32 v53, v230, v53, vcc
	v_cmp_le_i32_e32 vcc, v83, v0
	v_subrev_u32_e32 v83, 55, v82
	s_nop 0
	v_cndmask_b32_e32 v37, v230, v37, vcc
	v_cmp_le_i32_e32 vcc, v83, v0
	v_subrev_u32_e32 v83, 23, v82
	s_nop 0
	v_cndmask_b32_e32 v54, v230, v54, vcc
	v_cmp_le_i32_e32 vcc, v83, v0
	v_subrev_u32_e32 v83, 54, v82
	s_nop 0
	v_cndmask_b32_e32 v38, v230, v38, vcc
	v_cmp_le_i32_e32 vcc, v83, v0
	v_subrev_u32_e32 v83, 22, v82
	s_nop 0
	v_cndmask_b32_e32 v55, v230, v55, vcc
	v_cmp_le_i32_e32 vcc, v83, v0
	v_subrev_u32_e32 v83, 53, v82
	s_nop 0
	v_cndmask_b32_e32 v39, v230, v39, vcc
	v_cmp_le_i32_e32 vcc, v83, v0
	v_subrev_u32_e32 v83, 21, v82
	s_nop 0
	v_cndmask_b32_e32 v56, v230, v56, vcc
	v_cmp_le_i32_e32 vcc, v83, v0
	v_subrev_u32_e32 v83, 52, v82
	s_nop 0
	v_cndmask_b32_e32 v40, v230, v40, vcc
	v_cmp_le_i32_e32 vcc, v83, v0
	v_subrev_u32_e32 v83, 20, v82
	s_nop 0
	v_cndmask_b32_e32 v57, v230, v57, vcc
	v_cmp_le_i32_e32 vcc, v83, v0
	v_subrev_u32_e32 v83, 47, v82
	s_nop 0
	v_cndmask_b32_e32 v41, v230, v41, vcc
	v_cmp_le_i32_e32 vcc, v83, v0
	v_add_u32_e32 v83, -15, v82
	s_nop 0
	v_cndmask_b32_e32 v58, v230, v58, vcc
	v_cmp_le_i32_e32 vcc, v83, v0
	v_subrev_u32_e32 v83, 46, v82
	s_nop 0
	v_cndmask_b32_e32 v42, v230, v42, vcc
	v_cmp_le_i32_e32 vcc, v83, v0
	v_add_u32_e32 v83, -14, v82
	s_nop 0
	v_cndmask_b32_e32 v59, v230, v59, vcc
	v_cmp_le_i32_e32 vcc, v83, v0
	v_subrev_u32_e32 v83, 45, v82
	s_nop 0
	v_cndmask_b32_e32 v43, v230, v43, vcc
	v_cmp_le_i32_e32 vcc, v83, v0
	v_add_u32_e32 v83, -13, v82
	s_nop 0
	v_cndmask_b32_e32 v60, v230, v60, vcc
	v_cmp_le_i32_e32 vcc, v83, v0
	v_subrev_u32_e32 v83, 44, v82
	s_nop 0
	v_cndmask_b32_e32 v44, v230, v44, vcc
	v_cmp_le_i32_e32 vcc, v83, v0
	v_add_u32_e32 v83, -12, v82
	s_nop 0
	v_cndmask_b32_e32 v61, v230, v61, vcc
	v_cmp_le_i32_e32 vcc, v83, v0
	v_subrev_u32_e32 v83, 39, v82
	s_nop 0
	v_cndmask_b32_e32 v45, v230, v45, vcc
	v_cmp_le_i32_e32 vcc, v83, v0
	v_add_u32_e32 v83, -7, v82
	s_nop 0
	v_cndmask_b32_e32 v62, v230, v62, vcc
	v_cmp_le_i32_e32 vcc, v83, v0
	v_subrev_u32_e32 v83, 38, v82
	s_nop 0
	v_cndmask_b32_e32 v46, v230, v46, vcc
	v_cmp_le_i32_e32 vcc, v83, v0
	v_add_u32_e32 v83, -6, v82
	s_nop 0
	v_cndmask_b32_e32 v63, v230, v63, vcc
	v_cmp_le_i32_e32 vcc, v83, v0
	v_subrev_u32_e32 v83, 37, v82
	s_nop 0
	v_cndmask_b32_e32 v47, v230, v47, vcc
	v_cmp_le_i32_e32 vcc, v83, v0
	v_add_u32_e32 v83, -5, v82
	s_nop 0
	v_cndmask_b32_e32 v64, v230, v64, vcc
	v_cmp_le_i32_e32 vcc, v83, v0
	v_subrev_u32_e32 v83, 36, v82
	v_add_u32_e32 v82, -4, v82
	v_cndmask_b32_e32 v48, v230, v48, vcc
	v_cmp_le_i32_e32 vcc, v83, v0
	s_nop 1
	v_cndmask_b32_e32 v65, v230, v65, vcc
	v_cmp_le_i32_e32 vcc, v82, v0
	s_nop 1
	v_cndmask_b32_e32 v49, v230, v49, vcc

; template <int DV, int NMAP>
; __device__ __forceinline__ void attn_unit(LAS unsigned char* lds, const bf16_t* U, bf16_t* MIX, const float* logf, int b, int h, int qb, float lam, float slope2, const float* gn, float outscale, const int tid) {
;     ...
;         if (t + 2 < NT) AT_DMA(t + 2, st2);
;         if (64 * t <= qrow0 + 31) {
.Lfxl_inact:
	s_add_i32 s30, s64, 2
	s_cmp_ge_u32 s30, s37
	s_cbranch_scc1 .LBB0_203
	s_mul_i32 s30, s41, 0x2100
	s_add_i32 s30, s20, s30
	s_mov_b32 s31, m0
	s_mov_b32 m0, s30
	s_nop 0
	global_load_lds_dwordx4 v[102:103], off
	s_mov_b32 m0, s31
	s_lshl_b32 s30, s41, 13
	s_add_i32 s30, s30, s40
	s_mov_b32 s31, m0
	s_mov_b32 m0, s30
	s_nop 0
	global_load_lds_dwordx4 v[100:101], off
	s_mov_b32 m0, s31
	s_branch .LBB0_203
